# P6' row sums aggregated across the 4 column waves through LDS (4x fewer atomics) + one arrival/poller per workgroup; rest as v056
# speedup vs baseline: 1.0033x; 1.0019x over previous
.LBB0_677:
	s_lshl_b32 s3, s2, 8
	s_add_i32 s3, s3, s77
	v_add_u32_e32 v181, s3, v172
	v_lshl_add_u32 v185, v173, 3, s44
	v_lshlrev_b32_e32 v253, 2, v181
	v_lshlrev_b32_e32 v252, 2, v185
	v_lshlrev_b32_e32 v187, 12, v181
	v_lshl_add_u32 v187, v185, 1, v187
	v_lshlrev_b32_e32 v181, 13, v181
	s_lshl_b32 s3, s44, 2
	v_lshl_add_u32 v185, v173, 4, s3
	v_add_u32_e32 v185, v185, v181
	global_load_dword v164, v253, s[12:13]
	global_load_dword v165, v253, s[12:13] offset:64
	global_load_dword v166, v253, s[12:13] offset:128
	global_load_dword v167, v253, s[12:13] offset:192
	global_load_dword v168, v253, s[12:13] offset:512
	global_load_dword v169, v253, s[12:13] offset:576
	global_load_dword v170, v253, s[12:13] offset:640
	global_load_dword v171, v253, s[12:13] offset:704
	global_load_dwordx4 v[148:151], v252, s[14:15] offset:0
	global_load_dwordx4 v[152:155], v252, s[14:15] offset:16
	global_load_dwordx4 v[156:159], v252, s[14:15] offset:512
	global_load_dwordx4 v[160:163], v252, s[14:15] offset:528
	s_mov_b32 s98, s18
	s_mov_b32 s99, s19
	s_nop 0
	global_load_dwordx4 v[188:191], v187, s[98:99]
	global_load_dwordx4 v[192:195], v187, s[98:99] offset:256
	s_add_u32 s98, s18, 0x10000
	s_addc_u32 s99, s19, 0
	s_nop 0
	global_load_dwordx4 v[196:199], v187, s[98:99]
	global_load_dwordx4 v[200:203], v187, s[98:99] offset:256
	s_add_u32 s98, s18, 0x20000
	s_addc_u32 s99, s19, 0
	s_nop 0
	global_load_dwordx4 v[204:207], v187, s[98:99]
	global_load_dwordx4 v[208:211], v187, s[98:99] offset:256
	s_add_u32 s98, s18, 0x30000
	s_addc_u32 s99, s19, 0
	s_nop 0
	global_load_dwordx4 v[212:215], v187, s[98:99]
	global_load_dwordx4 v[216:219], v187, s[98:99] offset:256
	s_add_u32 s98, s18, 0x80000
	s_addc_u32 s99, s19, 0
	s_nop 0
	global_load_dwordx4 v[220:223], v187, s[98:99]
	global_load_dwordx4 v[224:227], v187, s[98:99] offset:256
	s_add_u32 s98, s18, 0x90000
	s_addc_u32 s99, s19, 0
	s_nop 0
	global_load_dwordx4 v[228:231], v187, s[98:99]
	global_load_dwordx4 v[232:235], v187, s[98:99] offset:256
	s_add_u32 s98, s18, 0xa0000
	s_addc_u32 s99, s19, 0
	s_nop 0
	global_load_dwordx4 v[236:239], v187, s[98:99]
	global_load_dwordx4 v[240:243], v187, s[98:99] offset:256
	s_add_u32 s98, s18, 0xb0000
	s_addc_u32 s99, s19, 0
	s_nop 0
	global_load_dwordx4 v[244:247], v187, s[98:99]
	global_load_dwordx4 v[248:251], v187, s[98:99] offset:256
	s_waitcnt vmcnt(15)
	v_fmamk_f32 v184, v164, 0x3a000000, v177
	v_rcp_f32_e32 v184, v184
	v_and_b32_e32 v129, 0xffff0000, v188
	v_lshlrev_b32_e32 v128, 16, v188
	v_and_b32_e32 v131, 0xffff0000, v189
	v_lshlrev_b32_e32 v130, 16, v189
	v_and_b32_e32 v133, 0xffff0000, v190
	v_lshlrev_b32_e32 v132, 16, v190
	v_and_b32_e32 v135, 0xffff0000, v191
	v_lshlrev_b32_e32 v134, 16, v191
	v_pk_mul_f32 v[128:129], v[148:149], v[128:129]
	v_pk_mul_f32 v[130:131], v[150:151], v[130:131]
	v_pk_mul_f32 v[132:133], v[152:153], v[132:133]
	v_pk_mul_f32 v[134:135], v[154:155], v[134:135]
	v_pk_fma_f32 v[124:125], v[124:125], v[184:185], v[128:129] op_sel_hi:[1,0,1]
	v_pk_fma_f32 v[126:127], v[126:127], v[184:185], v[130:131] op_sel_hi:[1,0,1]
	v_pk_fma_f32 v[120:121], v[120:121], v[184:185], v[132:133] op_sel_hi:[1,0,1]
	v_pk_fma_f32 v[122:123], v[122:123], v[184:185], v[134:135] op_sel_hi:[1,0,1]
	v_pk_mul_f32 v[182:183], v[124:125], v[124:125]
	v_pk_fma_f32 v[182:183], v[126:127], v[126:127], v[182:183]
	v_pk_fma_f32 v[182:183], v[120:121], v[120:121], v[182:183]
	v_pk_fma_f32 v[182:183], v[122:123], v[122:123], v[182:183]
	s_waitcnt vmcnt(14)
	v_and_b32_e32 v129, 0xffff0000, v192
	v_lshlrev_b32_e32 v128, 16, v192
	v_and_b32_e32 v131, 0xffff0000, v193
	v_lshlrev_b32_e32 v130, 16, v193
	v_and_b32_e32 v133, 0xffff0000, v194
	v_lshlrev_b32_e32 v132, 16, v194
	v_and_b32_e32 v135, 0xffff0000, v195
	v_lshlrev_b32_e32 v134, 16, v195
	v_pk_mul_f32 v[128:129], v[156:157], v[128:129]
	v_pk_mul_f32 v[130:131], v[158:159], v[130:131]
	v_pk_mul_f32 v[132:133], v[160:161], v[132:133]
	v_pk_mul_f32 v[134:135], v[162:163], v[134:135]
	v_pk_fma_f32 v[116:117], v[116:117], v[184:185], v[128:129] op_sel_hi:[1,0,1]
	v_pk_fma_f32 v[118:119], v[118:119], v[184:185], v[130:131] op_sel_hi:[1,0,1]
	v_pk_fma_f32 v[112:113], v[112:113], v[184:185], v[132:133] op_sel_hi:[1,0,1]
	v_pk_fma_f32 v[114:115], v[114:115], v[184:185], v[134:135] op_sel_hi:[1,0,1]
	v_pk_fma_f32 v[182:183], v[116:117], v[116:117], v[182:183]
	v_pk_fma_f32 v[182:183], v[118:119], v[118:119], v[182:183]
	v_pk_fma_f32 v[182:183], v[112:113], v[112:113], v[182:183]
	v_pk_fma_f32 v[182:183], v[114:115], v[114:115], v[182:183]
	v_add_f32_e32 v164, v182, v183
	s_waitcnt vmcnt(13)
	v_fmamk_f32 v184, v165, 0x3a000000, v177
	v_rcp_f32_e32 v184, v184
	v_and_b32_e32 v129, 0xffff0000, v196
	v_lshlrev_b32_e32 v128, 16, v196
	v_and_b32_e32 v131, 0xffff0000, v197
	v_lshlrev_b32_e32 v130, 16, v197
	v_and_b32_e32 v133, 0xffff0000, v198
	v_lshlrev_b32_e32 v132, 16, v198
	v_and_b32_e32 v135, 0xffff0000, v199
	v_lshlrev_b32_e32 v134, 16, v199
	v_pk_mul_f32 v[128:129], v[148:149], v[128:129]
	v_pk_mul_f32 v[130:131], v[150:151], v[130:131]
	v_pk_mul_f32 v[132:133], v[152:153], v[132:133]
	v_pk_mul_f32 v[134:135], v[154:155], v[134:135]
	v_pk_fma_f32 v[108:109], v[108:109], v[184:185], v[128:129] op_sel_hi:[1,0,1]
	v_pk_fma_f32 v[110:111], v[110:111], v[184:185], v[130:131] op_sel_hi:[1,0,1]
	v_pk_fma_f32 v[104:105], v[104:105], v[184:185], v[132:133] op_sel_hi:[1,0,1]
	v_pk_fma_f32 v[106:107], v[106:107], v[184:185], v[134:135] op_sel_hi:[1,0,1]
	v_pk_mul_f32 v[182:183], v[108:109], v[108:109]
	v_pk_fma_f32 v[182:183], v[110:111], v[110:111], v[182:183]
	v_pk_fma_f32 v[182:183], v[104:105], v[104:105], v[182:183]
	v_pk_fma_f32 v[182:183], v[106:107], v[106:107], v[182:183]
	s_waitcnt vmcnt(12)
	v_and_b32_e32 v129, 0xffff0000, v200
	v_lshlrev_b32_e32 v128, 16, v200
	v_and_b32_e32 v131, 0xffff0000, v201
	v_lshlrev_b32_e32 v130, 16, v201
	v_and_b32_e32 v133, 0xffff0000, v202
	v_lshlrev_b32_e32 v132, 16, v202
	v_and_b32_e32 v135, 0xffff0000, v203
	v_lshlrev_b32_e32 v134, 16, v203
	v_pk_mul_f32 v[128:129], v[156:157], v[128:129]
	v_pk_mul_f32 v[130:131], v[158:159], v[130:131]
	v_pk_mul_f32 v[132:133], v[160:161], v[132:133]
	v_pk_mul_f32 v[134:135], v[162:163], v[134:135]
	v_pk_fma_f32 v[100:101], v[100:101], v[184:185], v[128:129] op_sel_hi:[1,0,1]
	v_pk_fma_f32 v[102:103], v[102:103], v[184:185], v[130:131] op_sel_hi:[1,0,1]
	v_pk_fma_f32 v[96:97], v[96:97], v[184:185], v[132:133] op_sel_hi:[1,0,1]
	v_pk_fma_f32 v[98:99], v[98:99], v[184:185], v[134:135] op_sel_hi:[1,0,1]
	v_pk_fma_f32 v[182:183], v[100:101], v[100:101], v[182:183]
	v_pk_fma_f32 v[182:183], v[102:103], v[102:103], v[182:183]
	v_pk_fma_f32 v[182:183], v[96:97], v[96:97], v[182:183]
	v_pk_fma_f32 v[182:183], v[98:99], v[98:99], v[182:183]
	v_add_f32_e32 v165, v182, v183
	s_waitcnt vmcnt(11)
	v_fmamk_f32 v184, v166, 0x3a000000, v177
	v_rcp_f32_e32 v184, v184
	v_and_b32_e32 v129, 0xffff0000, v204
	v_lshlrev_b32_e32 v128, 16, v204
	v_and_b32_e32 v131, 0xffff0000, v205
	v_lshlrev_b32_e32 v130, 16, v205
	v_and_b32_e32 v133, 0xffff0000, v206
	v_lshlrev_b32_e32 v132, 16, v206
	v_and_b32_e32 v135, 0xffff0000, v207
	v_lshlrev_b32_e32 v134, 16, v207
	v_pk_mul_f32 v[128:129], v[148:149], v[128:129]
	v_pk_mul_f32 v[130:131], v[150:151], v[130:131]
	v_pk_mul_f32 v[132:133], v[152:153], v[132:133]
	v_pk_mul_f32 v[134:135], v[154:155], v[134:135]
	v_pk_fma_f32 v[92:93], v[92:93], v[184:185], v[128:129] op_sel_hi:[1,0,1]
	v_pk_fma_f32 v[94:95], v[94:95], v[184:185], v[130:131] op_sel_hi:[1,0,1]
	v_pk_fma_f32 v[88:89], v[88:89], v[184:185], v[132:133] op_sel_hi:[1,0,1]
	v_pk_fma_f32 v[90:91], v[90:91], v[184:185], v[134:135] op_sel_hi:[1,0,1]
	v_pk_mul_f32 v[182:183], v[92:93], v[92:93]
	v_pk_fma_f32 v[182:183], v[94:95], v[94:95], v[182:183]
	v_pk_fma_f32 v[182:183], v[88:89], v[88:89], v[182:183]
	v_pk_fma_f32 v[182:183], v[90:91], v[90:91], v[182:183]
	s_waitcnt vmcnt(10)
	v_and_b32_e32 v129, 0xffff0000, v208
	v_lshlrev_b32_e32 v128, 16, v208
	v_and_b32_e32 v131, 0xffff0000, v209
	v_lshlrev_b32_e32 v130, 16, v209
	v_and_b32_e32 v133, 0xffff0000, v210
	v_lshlrev_b32_e32 v132, 16, v210
	v_and_b32_e32 v135, 0xffff0000, v211
	v_lshlrev_b32_e32 v134, 16, v211
	v_pk_mul_f32 v[128:129], v[156:157], v[128:129]
	v_pk_mul_f32 v[130:131], v[158:159], v[130:131]
	v_pk_mul_f32 v[132:133], v[160:161], v[132:133]
	v_pk_mul_f32 v[134:135], v[162:163], v[134:135]
	v_pk_fma_f32 v[84:85], v[84:85], v[184:185], v[128:129] op_sel_hi:[1,0,1]
	v_pk_fma_f32 v[86:87], v[86:87], v[184:185], v[130:131] op_sel_hi:[1,0,1]
	v_pk_fma_f32 v[80:81], v[80:81], v[184:185], v[132:133] op_sel_hi:[1,0,1]
	v_pk_fma_f32 v[82:83], v[82:83], v[184:185], v[134:135] op_sel_hi:[1,0,1]
	v_pk_fma_f32 v[182:183], v[84:85], v[84:85], v[182:183]
	v_pk_fma_f32 v[182:183], v[86:87], v[86:87], v[182:183]
	v_pk_fma_f32 v[182:183], v[80:81], v[80:81], v[182:183]
	v_pk_fma_f32 v[182:183], v[82:83], v[82:83], v[182:183]
	v_add_f32_e32 v166, v182, v183
	s_waitcnt vmcnt(9)
	v_fmamk_f32 v184, v167, 0x3a000000, v177
	v_rcp_f32_e32 v184, v184
	v_and_b32_e32 v129, 0xffff0000, v212
	v_lshlrev_b32_e32 v128, 16, v212
	v_and_b32_e32 v131, 0xffff0000, v213
	v_lshlrev_b32_e32 v130, 16, v213
	v_and_b32_e32 v133, 0xffff0000, v214
	v_lshlrev_b32_e32 v132, 16, v214
	v_and_b32_e32 v135, 0xffff0000, v215
	v_lshlrev_b32_e32 v134, 16, v215
	v_pk_mul_f32 v[128:129], v[148:149], v[128:129]
	v_pk_mul_f32 v[130:131], v[150:151], v[130:131]
	v_pk_mul_f32 v[132:133], v[152:153], v[132:133]
	v_pk_mul_f32 v[134:135], v[154:155], v[134:135]
	v_pk_fma_f32 v[76:77], v[76:77], v[184:185], v[128:129] op_sel_hi:[1,0,1]
	v_pk_fma_f32 v[78:79], v[78:79], v[184:185], v[130:131] op_sel_hi:[1,0,1]
	v_pk_fma_f32 v[72:73], v[72:73], v[184:185], v[132:133] op_sel_hi:[1,0,1]
	v_pk_fma_f32 v[74:75], v[74:75], v[184:185], v[134:135] op_sel_hi:[1,0,1]
	v_pk_mul_f32 v[182:183], v[76:77], v[76:77]
	v_pk_fma_f32 v[182:183], v[78:79], v[78:79], v[182:183]
	v_pk_fma_f32 v[182:183], v[72:73], v[72:73], v[182:183]
	v_pk_fma_f32 v[182:183], v[74:75], v[74:75], v[182:183]
	s_waitcnt vmcnt(8)
	v_and_b32_e32 v129, 0xffff0000, v216
	v_lshlrev_b32_e32 v128, 16, v216
	v_and_b32_e32 v131, 0xffff0000, v217
	v_lshlrev_b32_e32 v130, 16, v217
	v_and_b32_e32 v133, 0xffff0000, v218
	v_lshlrev_b32_e32 v132, 16, v218
	v_and_b32_e32 v135, 0xffff0000, v219
	v_lshlrev_b32_e32 v134, 16, v219
	v_pk_mul_f32 v[128:129], v[156:157], v[128:129]
	v_pk_mul_f32 v[130:131], v[158:159], v[130:131]
	v_pk_mul_f32 v[132:133], v[160:161], v[132:133]
	v_pk_mul_f32 v[134:135], v[162:163], v[134:135]
	v_pk_fma_f32 v[68:69], v[68:69], v[184:185], v[128:129] op_sel_hi:[1,0,1]
	v_pk_fma_f32 v[70:71], v[70:71], v[184:185], v[130:131] op_sel_hi:[1,0,1]
	v_pk_fma_f32 v[64:65], v[64:65], v[184:185], v[132:133] op_sel_hi:[1,0,1]
	v_pk_fma_f32 v[66:67], v[66:67], v[184:185], v[134:135] op_sel_hi:[1,0,1]
	v_pk_fma_f32 v[182:183], v[68:69], v[68:69], v[182:183]
	v_pk_fma_f32 v[182:183], v[70:71], v[70:71], v[182:183]
	v_pk_fma_f32 v[182:183], v[64:65], v[64:65], v[182:183]
	v_pk_fma_f32 v[182:183], v[66:67], v[66:67], v[182:183]
	v_add_f32_e32 v167, v182, v183
	s_waitcnt vmcnt(7)
	v_fmamk_f32 v184, v168, 0x3a000000, v177
	v_rcp_f32_e32 v184, v184
	v_and_b32_e32 v129, 0xffff0000, v220
	v_lshlrev_b32_e32 v128, 16, v220
	v_and_b32_e32 v131, 0xffff0000, v221
	v_lshlrev_b32_e32 v130, 16, v221
	v_and_b32_e32 v133, 0xffff0000, v222
	v_lshlrev_b32_e32 v132, 16, v222
	v_and_b32_e32 v135, 0xffff0000, v223
	v_lshlrev_b32_e32 v134, 16, v223
	v_pk_mul_f32 v[128:129], v[148:149], v[128:129]
	v_pk_mul_f32 v[130:131], v[150:151], v[130:131]
	v_pk_mul_f32 v[132:133], v[152:153], v[132:133]
	v_pk_mul_f32 v[134:135], v[154:155], v[134:135]
	v_pk_fma_f32 v[60:61], v[60:61], v[184:185], v[128:129] op_sel_hi:[1,0,1]
	v_pk_fma_f32 v[62:63], v[62:63], v[184:185], v[130:131] op_sel_hi:[1,0,1]
	v_pk_fma_f32 v[56:57], v[56:57], v[184:185], v[132:133] op_sel_hi:[1,0,1]
	v_pk_fma_f32 v[58:59], v[58:59], v[184:185], v[134:135] op_sel_hi:[1,0,1]
	v_pk_mul_f32 v[182:183], v[60:61], v[60:61]
	v_pk_fma_f32 v[182:183], v[62:63], v[62:63], v[182:183]
	v_pk_fma_f32 v[182:183], v[56:57], v[56:57], v[182:183]
	v_pk_fma_f32 v[182:183], v[58:59], v[58:59], v[182:183]
	s_waitcnt vmcnt(6)
	v_and_b32_e32 v129, 0xffff0000, v224
	v_lshlrev_b32_e32 v128, 16, v224
	v_and_b32_e32 v131, 0xffff0000, v225
	v_lshlrev_b32_e32 v130, 16, v225
	v_and_b32_e32 v133, 0xffff0000, v226
	v_lshlrev_b32_e32 v132, 16, v226
	v_and_b32_e32 v135, 0xffff0000, v227
	v_lshlrev_b32_e32 v134, 16, v227
	v_pk_mul_f32 v[128:129], v[156:157], v[128:129]
	v_pk_mul_f32 v[130:131], v[158:159], v[130:131]
	v_pk_mul_f32 v[132:133], v[160:161], v[132:133]
	v_pk_mul_f32 v[134:135], v[162:163], v[134:135]
	v_pk_fma_f32 v[52:53], v[52:53], v[184:185], v[128:129] op_sel_hi:[1,0,1]
	v_pk_fma_f32 v[54:55], v[54:55], v[184:185], v[130:131] op_sel_hi:[1,0,1]
	v_pk_fma_f32 v[48:49], v[48:49], v[184:185], v[132:133] op_sel_hi:[1,0,1]
	v_pk_fma_f32 v[50:51], v[50:51], v[184:185], v[134:135] op_sel_hi:[1,0,1]
	v_pk_fma_f32 v[182:183], v[52:53], v[52:53], v[182:183]
	v_pk_fma_f32 v[182:183], v[54:55], v[54:55], v[182:183]
	v_pk_fma_f32 v[182:183], v[48:49], v[48:49], v[182:183]
	v_pk_fma_f32 v[182:183], v[50:51], v[50:51], v[182:183]
	v_add_f32_e32 v168, v182, v183
	s_waitcnt vmcnt(5)
	v_fmamk_f32 v184, v169, 0x3a000000, v177
	v_rcp_f32_e32 v184, v184
	v_and_b32_e32 v129, 0xffff0000, v228
	v_lshlrev_b32_e32 v128, 16, v228
	v_and_b32_e32 v131, 0xffff0000, v229
	v_lshlrev_b32_e32 v130, 16, v229
	v_and_b32_e32 v133, 0xffff0000, v230
	v_lshlrev_b32_e32 v132, 16, v230
	v_and_b32_e32 v135, 0xffff0000, v231
	v_lshlrev_b32_e32 v134, 16, v231
	v_pk_mul_f32 v[128:129], v[148:149], v[128:129]
	v_pk_mul_f32 v[130:131], v[150:151], v[130:131]
	v_pk_mul_f32 v[132:133], v[152:153], v[132:133]
	v_pk_mul_f32 v[134:135], v[154:155], v[134:135]
	v_pk_fma_f32 v[44:45], v[44:45], v[184:185], v[128:129] op_sel_hi:[1,0,1]
	v_pk_fma_f32 v[46:47], v[46:47], v[184:185], v[130:131] op_sel_hi:[1,0,1]
	v_pk_fma_f32 v[40:41], v[40:41], v[184:185], v[132:133] op_sel_hi:[1,0,1]
	v_pk_fma_f32 v[42:43], v[42:43], v[184:185], v[134:135] op_sel_hi:[1,0,1]
	v_pk_mul_f32 v[182:183], v[44:45], v[44:45]
	v_pk_fma_f32 v[182:183], v[46:47], v[46:47], v[182:183]
	v_pk_fma_f32 v[182:183], v[40:41], v[40:41], v[182:183]
	v_pk_fma_f32 v[182:183], v[42:43], v[42:43], v[182:183]
	s_waitcnt vmcnt(4)
	v_and_b32_e32 v129, 0xffff0000, v232
	v_lshlrev_b32_e32 v128, 16, v232
	v_and_b32_e32 v131, 0xffff0000, v233
	v_lshlrev_b32_e32 v130, 16, v233
	v_and_b32_e32 v133, 0xffff0000, v234
	v_lshlrev_b32_e32 v132, 16, v234
	v_and_b32_e32 v135, 0xffff0000, v235
	v_lshlrev_b32_e32 v134, 16, v235
	v_pk_mul_f32 v[128:129], v[156:157], v[128:129]
	v_pk_mul_f32 v[130:131], v[158:159], v[130:131]
	v_pk_mul_f32 v[132:133], v[160:161], v[132:133]
	v_pk_mul_f32 v[134:135], v[162:163], v[134:135]
	v_pk_fma_f32 v[36:37], v[36:37], v[184:185], v[128:129] op_sel_hi:[1,0,1]
	v_pk_fma_f32 v[38:39], v[38:39], v[184:185], v[130:131] op_sel_hi:[1,0,1]
	v_pk_fma_f32 v[32:33], v[32:33], v[184:185], v[132:133] op_sel_hi:[1,0,1]
	v_pk_fma_f32 v[34:35], v[34:35], v[184:185], v[134:135] op_sel_hi:[1,0,1]
	v_pk_fma_f32 v[182:183], v[36:37], v[36:37], v[182:183]
	v_pk_fma_f32 v[182:183], v[38:39], v[38:39], v[182:183]
	v_pk_fma_f32 v[182:183], v[32:33], v[32:33], v[182:183]
	v_pk_fma_f32 v[182:183], v[34:35], v[34:35], v[182:183]
	v_add_f32_e32 v169, v182, v183
	s_waitcnt vmcnt(3)
	v_fmamk_f32 v184, v170, 0x3a000000, v177
	v_rcp_f32_e32 v184, v184
	v_and_b32_e32 v129, 0xffff0000, v236
	v_lshlrev_b32_e32 v128, 16, v236
	v_and_b32_e32 v131, 0xffff0000, v237
	v_lshlrev_b32_e32 v130, 16, v237
	v_and_b32_e32 v133, 0xffff0000, v238
	v_lshlrev_b32_e32 v132, 16, v238
	v_and_b32_e32 v135, 0xffff0000, v239
	v_lshlrev_b32_e32 v134, 16, v239
	v_pk_mul_f32 v[128:129], v[148:149], v[128:129]
	v_pk_mul_f32 v[130:131], v[150:151], v[130:131]
	v_pk_mul_f32 v[132:133], v[152:153], v[132:133]
	v_pk_mul_f32 v[134:135], v[154:155], v[134:135]
	v_pk_fma_f32 v[28:29], v[28:29], v[184:185], v[128:129] op_sel_hi:[1,0,1]
	v_pk_fma_f32 v[30:31], v[30:31], v[184:185], v[130:131] op_sel_hi:[1,0,1]
	v_pk_fma_f32 v[24:25], v[24:25], v[184:185], v[132:133] op_sel_hi:[1,0,1]
	v_pk_fma_f32 v[26:27], v[26:27], v[184:185], v[134:135] op_sel_hi:[1,0,1]
	v_pk_mul_f32 v[182:183], v[28:29], v[28:29]
	v_pk_fma_f32 v[182:183], v[30:31], v[30:31], v[182:183]
	v_pk_fma_f32 v[182:183], v[24:25], v[24:25], v[182:183]
	v_pk_fma_f32 v[182:183], v[26:27], v[26:27], v[182:183]
	s_waitcnt vmcnt(2)
	v_and_b32_e32 v129, 0xffff0000, v240
	v_lshlrev_b32_e32 v128, 16, v240
	v_and_b32_e32 v131, 0xffff0000, v241
	v_lshlrev_b32_e32 v130, 16, v241
	v_and_b32_e32 v133, 0xffff0000, v242
	v_lshlrev_b32_e32 v132, 16, v242
	v_and_b32_e32 v135, 0xffff0000, v243
	v_lshlrev_b32_e32 v134, 16, v243
	v_pk_mul_f32 v[128:129], v[156:157], v[128:129]
	v_pk_mul_f32 v[130:131], v[158:159], v[130:131]
	v_pk_mul_f32 v[132:133], v[160:161], v[132:133]
	v_pk_mul_f32 v[134:135], v[162:163], v[134:135]
	v_pk_fma_f32 v[20:21], v[20:21], v[184:185], v[128:129] op_sel_hi:[1,0,1]
	v_pk_fma_f32 v[22:23], v[22:23], v[184:185], v[130:131] op_sel_hi:[1,0,1]
	v_pk_fma_f32 v[16:17], v[16:17], v[184:185], v[132:133] op_sel_hi:[1,0,1]
	v_pk_fma_f32 v[18:19], v[18:19], v[184:185], v[134:135] op_sel_hi:[1,0,1]
	v_pk_fma_f32 v[182:183], v[20:21], v[20:21], v[182:183]
	v_pk_fma_f32 v[182:183], v[22:23], v[22:23], v[182:183]
	v_pk_fma_f32 v[182:183], v[16:17], v[16:17], v[182:183]
	v_pk_fma_f32 v[182:183], v[18:19], v[18:19], v[182:183]
	v_add_f32_e32 v170, v182, v183
	s_waitcnt vmcnt(1)
	v_fmamk_f32 v184, v171, 0x3a000000, v177
	v_rcp_f32_e32 v184, v184
	v_and_b32_e32 v129, 0xffff0000, v244
	v_lshlrev_b32_e32 v128, 16, v244
	v_and_b32_e32 v131, 0xffff0000, v245
	v_lshlrev_b32_e32 v130, 16, v245
	v_and_b32_e32 v133, 0xffff0000, v246
	v_lshlrev_b32_e32 v132, 16, v246
	v_and_b32_e32 v135, 0xffff0000, v247
	v_lshlrev_b32_e32 v134, 16, v247
	v_pk_mul_f32 v[128:129], v[148:149], v[128:129]
	v_pk_mul_f32 v[130:131], v[150:151], v[130:131]
	v_pk_mul_f32 v[132:133], v[152:153], v[132:133]
	v_pk_mul_f32 v[134:135], v[154:155], v[134:135]
	v_pk_fma_f32 v[12:13], v[12:13], v[184:185], v[128:129] op_sel_hi:[1,0,1]
	v_pk_fma_f32 v[14:15], v[14:15], v[184:185], v[130:131] op_sel_hi:[1,0,1]
	v_pk_fma_f32 v[8:9], v[8:9], v[184:185], v[132:133] op_sel_hi:[1,0,1]
	v_pk_fma_f32 v[10:11], v[10:11], v[184:185], v[134:135] op_sel_hi:[1,0,1]
	v_pk_mul_f32 v[182:183], v[12:13], v[12:13]
	v_pk_fma_f32 v[182:183], v[14:15], v[14:15], v[182:183]
	v_pk_fma_f32 v[182:183], v[8:9], v[8:9], v[182:183]
	v_pk_fma_f32 v[182:183], v[10:11], v[10:11], v[182:183]
	s_waitcnt vmcnt(0)
	v_and_b32_e32 v129, 0xffff0000, v248
	v_lshlrev_b32_e32 v128, 16, v248
	v_and_b32_e32 v131, 0xffff0000, v249
	v_lshlrev_b32_e32 v130, 16, v249
	v_and_b32_e32 v133, 0xffff0000, v250
	v_lshlrev_b32_e32 v132, 16, v250
	v_and_b32_e32 v135, 0xffff0000, v251
	v_lshlrev_b32_e32 v134, 16, v251
	v_pk_mul_f32 v[128:129], v[156:157], v[128:129]
	v_pk_mul_f32 v[130:131], v[158:159], v[130:131]
	v_pk_mul_f32 v[132:133], v[160:161], v[132:133]
	v_pk_mul_f32 v[134:135], v[162:163], v[134:135]
	v_pk_fma_f32 v[4:5], v[4:5], v[184:185], v[128:129] op_sel_hi:[1,0,1]
	v_pk_fma_f32 v[6:7], v[6:7], v[184:185], v[130:131] op_sel_hi:[1,0,1]
	v_pk_fma_f32 v[0:1], v[0:1], v[184:185], v[132:133] op_sel_hi:[1,0,1]
	v_pk_fma_f32 v[2:3], v[2:3], v[184:185], v[134:135] op_sel_hi:[1,0,1]
	v_pk_fma_f32 v[182:183], v[4:5], v[4:5], v[182:183]
	v_pk_fma_f32 v[182:183], v[6:7], v[6:7], v[182:183]
	v_pk_fma_f32 v[182:183], v[0:1], v[0:1], v[182:183]
	v_pk_fma_f32 v[182:183], v[2:3], v[2:3], v[182:183]
	v_add_f32_e32 v171, v182, v183
	global_load_dwordx4 v[148:151], v252, s[86:87] offset:0
	global_load_dwordx4 v[152:155], v252, s[86:87] offset:16
	global_load_dwordx4 v[156:159], v252, s[86:87] offset:512
	global_load_dwordx4 v[160:163], v252, s[86:87] offset:528
	v_xor_b32_e32 v128, 16, v186
	v_xor_b32_e32 v129, 32, v186
	v_lshlrev_b32_e32 v128, 2, v128
	v_lshlrev_b32_e32 v129, 2, v129
	ds_bpermute_b32 v188, v128, v164
	ds_bpermute_b32 v189, v128, v165
	ds_bpermute_b32 v190, v128, v166
	ds_bpermute_b32 v191, v128, v167
	ds_bpermute_b32 v192, v128, v168
	ds_bpermute_b32 v193, v128, v169
	ds_bpermute_b32 v194, v128, v170
	ds_bpermute_b32 v195, v128, v171
	s_waitcnt lgkmcnt(7)
	v_add_f32_e32 v164, v164, v188
	s_waitcnt lgkmcnt(6)
	v_add_f32_e32 v165, v165, v189
	s_waitcnt lgkmcnt(5)
	v_add_f32_e32 v166, v166, v190
	s_waitcnt lgkmcnt(4)
	v_add_f32_e32 v167, v167, v191
	s_waitcnt lgkmcnt(3)
	v_add_f32_e32 v168, v168, v192
	s_waitcnt lgkmcnt(2)
	v_add_f32_e32 v169, v169, v193
	s_waitcnt lgkmcnt(1)
	v_add_f32_e32 v170, v170, v194
	s_waitcnt lgkmcnt(0)
	v_add_f32_e32 v171, v171, v195
	ds_bpermute_b32 v188, v129, v164
	ds_bpermute_b32 v189, v129, v165
	ds_bpermute_b32 v190, v129, v166
	ds_bpermute_b32 v191, v129, v167
	ds_bpermute_b32 v192, v129, v168
	ds_bpermute_b32 v193, v129, v169
	ds_bpermute_b32 v194, v129, v170
	ds_bpermute_b32 v195, v129, v171
	s_waitcnt lgkmcnt(7)
	v_add_f32_e32 v164, v164, v188
	s_waitcnt lgkmcnt(6)
	v_add_f32_e32 v165, v165, v189
	s_waitcnt lgkmcnt(5)
	v_add_f32_e32 v166, v166, v190
	s_waitcnt lgkmcnt(4)
	v_add_f32_e32 v167, v167, v191
	s_waitcnt lgkmcnt(3)
	v_add_f32_e32 v168, v168, v192
	s_waitcnt lgkmcnt(2)
	v_add_f32_e32 v169, v169, v193
	s_waitcnt lgkmcnt(1)
	v_add_f32_e32 v170, v170, v194
	s_waitcnt lgkmcnt(0)
	v_add_f32_e32 v171, v171, v195
	v_readlane_b32 s29, v254, 6
	s_nop 3
	s_lshl_b32 s30, s29, 3
	s_and_b32 s31, s29, 0x100
	s_lshl_b32 s31, s31, 3
	s_bfe_u32 s36, s29, 0x20006
	s_lshl_b32 s37, s36, 7
	s_add_i32 s31, s31, s37
	v_lshlrev_b32_e32 v128, 2, v172
	v_add_u32_e32 v128, 0x20800, v128
	v_add_u32_e32 v129, s31, v128
	v_add_u32_e32 v128, s30, v128
	v_cmp_eq_u32_e32 vcc, 0, v173
	s_and_saveexec_b64 s[36:37], vcc
	ds_write_b32 v128, v164 offset:0
	ds_write_b32 v128, v165 offset:64
	ds_write_b32 v128, v166 offset:128
	ds_write_b32 v128, v167 offset:192
	ds_write_b32 v128, v168 offset:256
	ds_write_b32 v128, v169 offset:320
	ds_write_b32 v128, v170 offset:384
	ds_write_b32 v128, v171 offset:448
	s_waitcnt lgkmcnt(0)
	s_or_b64 exec, exec, s[36:37]
	s_barrier
	s_and_saveexec_b64 s[36:37], vcc
	ds_read_b32 v188, v129 offset:0
	ds_read_b32 v189, v129 offset:512
	ds_read_b32 v190, v129 offset:1024
	ds_read_b32 v191, v129 offset:1536
	ds_read_b32 v192, v129 offset:64
	ds_read_b32 v193, v129 offset:576
	ds_read_b32 v194, v129 offset:1088
	ds_read_b32 v195, v129 offset:1600
	s_bfe_u32 s30, s29, 0x20006
	s_and_b32 s31, s30, 1
	s_lshl_b32 s31, s31, 7
	s_lshr_b32 s30, s30, 1
	s_lshl_b32 s30, s30, 9
	s_add_i32 s30, s30, s31
	v_add_u32_e32 v128, s30, v253
	s_waitcnt lgkmcnt(0)
	v_add_f32_e32 v188, v188, v189
	v_add_f32_e32 v190, v190, v191
	v_add_f32_e32 v188, v188, v190
	global_atomic_add_f32 v128, v188, s[16:17]
	v_add_f32_e32 v192, v192, v193
	v_add_f32_e32 v194, v194, v195
	v_add_f32_e32 v192, v192, v194
	global_atomic_add_f32 v128, v192, s[16:17] offset:64
	s_or_b64 exec, exec, s[36:37]
	s_lshl_b32 s2, s2, 6
	s_ashr_i32 s3, s2, 31
	s_lshl_b64 s[2:3], s[2:3], 2
	s_waitcnt vmcnt(0)
	s_add_u32 s24, s42, s2
	s_addc_u32 s25, s43, s3
	s_barrier
	v_readlane_b32 s2, v254, 6
	s_nop 3
	s_cmp_lg_u32 s2, 0
	s_cbranch_scc1 .Lp6_poll_done
	v_mov_b32_e32 v181, 1
	s_mov_b64 s[2:3], exec
	s_mov_b64 exec, 1
	global_atomic_add v139, v181, s[24:25]
	s_mov_b64 exec, s[2:3]
	s_mov_b32 s29, 0x100001
